# window branch: hand-pipelined two-block step (QK of block b overlapped with exp of block a, no row masks) for interior double tiles
# speedup vs baseline: 1.0166x; 1.0031x over previous
.LBB0_1368:
	s_and_b32 s17, s16, 1
	s_mul_i32 s2, s17, 0x4800
	s_add_i32 s21, s2, 0
	s_mul_i32 s2, s17, 0x1800
	s_add_i32 s22, s21, s2
	s_cmp_le_u32 s10, s0
	s_cbranch_scc1 .Lwin_generic
	s_add_i32 s2, s10, 1
	s_cmp_ge_u32 s2, s20
	s_cbranch_scc1 .Lwin_generic
	v_cmp_neq_f32_e32 vcc, 0, v178
	s_cmp_lg_u64 vcc, 0
	s_cbranch_scc0 .Lwin_att2
.Lwin_generic:
	s_cmp_lt_u32 s10, s0
	s_cselect_b64 s[2:3], -1, 0
	s_cmp_gt_u32 s10, s20
	s_cselect_b64 s[6:7], -1, 0
	s_or_b64 s[2:3], s[2:3], s[6:7]
	s_and_b64 vcc, exec, s[2:3]
	s_cbranch_vccnz .LBB0_1381
	s_cmp_lg_u32 s0, s10
	s_cselect_b64 s[2:3], -1, 0
	s_cmp_lg_u32 s20, s10
	s_cselect_b64 s[6:7], -1, 0
	s_and_b64 s[2:3], s[2:3], s[6:7]
	s_mov_b64 s[6:7], -1
	s_and_b64 vcc, exec, s[2:3]
	v_cmp_neq_f32_e64 s[2:3], 0, v178
	s_cbranch_vccz .LBB0_1374
	v_add3_u32 v2, s21, v137, v172
	ds_read_b128 v[36:39], v2
	ds_read_b128 v[92:95], v2 offset:32
	ds_read_b128 v[40:43], v2 offset:4608
	ds_read_b128 v[100:103], v2 offset:4640
	ds_read_b128 v[104:107], v2 offset:64
	ds_read_b128 v[130:133], v2 offset:96
	ds_read_b128 v[140:143], v2 offset:4672
	ds_read_b128 v[144:147], v2 offset:4704
	v_add_u32_e32 v2, s22, v173
	v_add_u32_e32 v2, v2, v174
	ds_read_b64_tr_b16 v[108:109], v2 offset:36864
	ds_read_b64_tr_b16 v[110:111], v2 offset:38400
	ds_read_b64_tr_b16 v[98:99], v2 offset:38464
	ds_read_b64_tr_b16 v[96:97], v2 offset:36928
	ds_read_b64_tr_b16 v[88:89], v2 offset:39936
	ds_read_b64_tr_b16 v[90:91], v2 offset:41472
	ds_read_b64_tr_b16 v[86:87], v2 offset:41536
	ds_read_b64_tr_b16 v[84:85], v2 offset:40000
	s_waitcnt lgkmcnt(14)
	v_mfma_f32_32x32x16_bf16 v[52:67], v[36:39], v[114:117], 0
	s_mov_b64 vcc, s[2:3]
	s_waitcnt lgkmcnt(13)
	v_mfma_f32_32x32x16_bf16 v[36:51], v[40:43], v[114:117], 0
	v_mfma_f32_32x32x16_bf16 v[52:67], v[92:95], v[118:121], v[52:67]
	s_waitcnt lgkmcnt(12)
	v_mfma_f32_32x32x16_bf16 v[36:51], v[100:103], v[118:121], v[36:51]
	s_waitcnt lgkmcnt(11)
	v_mfma_f32_32x32x16_bf16 v[52:67], v[104:107], v[122:125], v[52:67]
	s_waitcnt lgkmcnt(9)
	v_mfma_f32_32x32x16_bf16 v[36:51], v[140:143], v[122:125], v[36:51]
	v_mfma_f32_32x32x16_bf16 v[52:67], v[130:133], v[126:129], v[52:67]
	s_waitcnt lgkmcnt(8)
	v_mfma_f32_32x32x16_bf16 v[36:51], v[144:147], v[126:129], v[36:51]
	s_cbranch_vccz .LBB0_1372
	s_nop 8
	v_sub_f32_e32 v67, v67, v178
	v_sub_f32_e32 v66, v66, v178
	v_sub_f32_e32 v65, v65, v178
	v_sub_f32_e32 v64, v64, v178
	v_sub_f32_e32 v63, v63, v178
	v_sub_f32_e32 v62, v62, v178
	v_sub_f32_e32 v61, v61, v178
	v_sub_f32_e32 v60, v60, v178
	v_sub_f32_e32 v59, v59, v178
	v_sub_f32_e32 v58, v58, v178
	v_sub_f32_e32 v57, v57, v178
	v_sub_f32_e32 v56, v56, v178
	v_sub_f32_e32 v55, v55, v178
	v_sub_f32_e32 v54, v54, v178
	v_sub_f32_e32 v53, v53, v178
	v_sub_f32_e32 v52, v52, v178
	v_sub_f32_e32 v51, v51, v178
	v_sub_f32_e32 v50, v50, v178
	v_sub_f32_e32 v49, v49, v178
	v_sub_f32_e32 v48, v48, v178
	v_sub_f32_e32 v47, v47, v178
	v_sub_f32_e32 v46, v46, v178
	v_sub_f32_e32 v45, v45, v178
	v_sub_f32_e32 v44, v44, v178
	v_sub_f32_e32 v43, v43, v178
	v_sub_f32_e32 v42, v42, v178
	v_sub_f32_e32 v41, v41, v178
	v_sub_f32_e32 v40, v40, v178
	v_sub_f32_e32 v39, v39, v178
	v_sub_f32_e32 v38, v38, v178
	v_sub_f32_e32 v37, v37, v178
	v_sub_f32_e32 v36, v36, v178

.Lwin_att2:
	v_add3_u32 v2, s21, v137, v172
	v_add_u32_e32 v244, s22, v173
	v_add_u32_e32 v244, v244, v174
	ds_read_b128 v[36:39], v2
	ds_read_b128 v[40:43], v2 offset:32
	ds_read_b128 v[44:47], v2 offset:64
	ds_read_b128 v[48:51], v2 offset:96
	ds_read_b128 v[52:55], v2 offset:4608
	ds_read_b128 v[56:59], v2 offset:4640
	ds_read_b128 v[60:63], v2 offset:4672
	ds_read_b128 v[64:67], v2 offset:4704
	s_waitcnt lgkmcnt(7)
	v_mfma_f32_32x32x16_bf16 v[204:219], v[36:39], v[114:117], 0
	ds_read_b128 v[140:143], v2 offset:9216
	ds_read_b128 v[144:147], v2 offset:9248
	s_waitcnt lgkmcnt(8)
	v_mfma_f32_32x32x16_bf16 v[204:219], v[40:43], v[118:121], v[204:219]
	ds_read_b128 v[148:151], v2 offset:9280
	ds_read_b128 v[152:155], v2 offset:9312
	s_waitcnt lgkmcnt(9)
	v_mfma_f32_32x32x16_bf16 v[204:219], v[44:47], v[122:125], v[204:219]
	ds_read_b128 v[156:159], v2 offset:13824
	ds_read_b128 v[160:163], v2 offset:13856
	s_waitcnt lgkmcnt(10)
	v_mfma_f32_32x32x16_bf16 v[204:219], v[48:51], v[126:129], v[204:219]
	ds_read_b128 v[164:167], v2 offset:13888
	ds_read_b128 v[168:171], v2 offset:13920
	s_nop 7
	s_waitcnt lgkmcnt(11)
	v_mfma_f32_32x32x16_bf16 v[220:235], v[52:55], v[114:117], 0
	ds_read_b64_tr_b16 v[84:85], v244 offset:36864
	ds_read_b64_tr_b16 v[86:87], v244 offset:38400
	v_exp_f32_e32 v236, v204
	v_exp_f32_e32 v237, v205
	v_exp_f32_e32 v238, v206
	v_exp_f32_e32 v239, v207
	v_exp_f32_e32 v240, v208
	v_exp_f32_e32 v241, v209
	v_exp_f32_e32 v242, v210
	s_waitcnt lgkmcnt(12)
	v_mfma_f32_32x32x16_bf16 v[220:235], v[56:59], v[118:121], v[220:235]
	ds_read_b64_tr_b16 v[88:89], v244 offset:36928
	ds_read_b64_tr_b16 v[90:91], v244 offset:38464
	v_exp_f32_e32 v243, v211
	v_cvt_pk_bf16_f32 v180, v236, v237
	v_cvt_pk_bf16_f32 v181, v238, v239
	v_cvt_pk_bf16_f32 v182, v240, v241
	v_cvt_pk_bf16_f32 v183, v242, v243
	v_add_f32_e32 v236, v236, v237
	v_add_f32_e32 v238, v238, v239
	v_add_f32_e32 v240, v240, v241
	s_waitcnt lgkmcnt(13)
	v_mfma_f32_32x32x16_bf16 v[220:235], v[60:63], v[122:125], v[220:235]
	ds_read_b64_tr_b16 v[92:93], v244 offset:39936
	s_waitcnt lgkmcnt(12)
	ds_read_b64_tr_b16 v[94:95], v244 offset:41472
	v_add_f32_e32 v242, v242, v243
	v_add_f32_e32 v236, v236, v238
	v_add_f32_e32 v240, v240, v242
	v_add_f32_e32 v196, v236, v240
	v_mfma_f32_32x32x16_bf16 v[220:235], v[64:67], v[126:129], v[220:235]
	ds_read_b64_tr_b16 v[96:97], v244 offset:40000
	s_waitcnt lgkmcnt(12)
	ds_read_b64_tr_b16 v[98:99], v244 offset:41536
	v_exp_f32_e32 v236, v212
	v_exp_f32_e32 v237, v213
	v_exp_f32_e32 v238, v214
	v_exp_f32_e32 v239, v215
	v_exp_f32_e32 v240, v216
	v_exp_f32_e32 v241, v217
	v_exp_f32_e32 v242, v218
	v_exp_f32_e32 v243, v219
	v_mfma_f32_32x32x16_bf16 v[36:51], v[140:143], v[114:117], 0
	ds_read_b64_tr_b16 v[100:101], v244 offset:43008
	s_waitcnt lgkmcnt(12)
	ds_read_b64_tr_b16 v[102:103], v244 offset:44544
	v_cvt_pk_bf16_f32 v184, v236, v237
	v_cvt_pk_bf16_f32 v185, v238, v239
	v_cvt_pk_bf16_f32 v186, v240, v241
	v_cvt_pk_bf16_f32 v187, v242, v243
	v_add_f32_e32 v236, v236, v237
	v_add_f32_e32 v238, v238, v239
	v_add_f32_e32 v240, v240, v241
	v_add_f32_e32 v242, v242, v243
	v_mfma_f32_32x32x16_bf16 v[36:51], v[144:147], v[118:121], v[36:51]
	ds_read_b64_tr_b16 v[104:105], v244 offset:43072
	s_waitcnt lgkmcnt(12)
	ds_read_b64_tr_b16 v[106:107], v244 offset:44608
	v_add_f32_e32 v236, v236, v238
	v_add_f32_e32 v240, v240, v242
	v_add_f32_e32 v236, v236, v240
	v_add_f32_e32 v196, v196, v236
	v_mfma_f32_32x32x16_bf16 v[36:51], v[148:151], v[122:125], v[36:51]
	ds_read_b64_tr_b16 v[108:109], v244 offset:46080
	s_waitcnt lgkmcnt(12)
	ds_read_b64_tr_b16 v[110:111], v244 offset:47616
	ds_read_b64_tr_b16 v[204:205], v244 offset:49152
	s_waitcnt lgkmcnt(12)
	ds_read_b64_tr_b16 v[206:207], v244 offset:50688
	v_exp_f32_e32 v236, v220
	v_exp_f32_e32 v237, v221
	v_exp_f32_e32 v238, v222
	v_exp_f32_e32 v239, v223
	v_exp_f32_e32 v240, v224
	v_exp_f32_e32 v241, v225
	v_exp_f32_e32 v242, v226
	v_exp_f32_e32 v243, v227
	v_mfma_f32_32x32x16_bf16 v[36:51], v[152:155], v[126:129], v[36:51]
	ds_read_b64_tr_b16 v[130:131], v244 offset:46144
	s_waitcnt lgkmcnt(12)
	ds_read_b64_tr_b16 v[132:133], v244 offset:47680
	ds_read_b64_tr_b16 v[208:209], v244 offset:49216
	s_waitcnt lgkmcnt(12)
	ds_read_b64_tr_b16 v[210:211], v244 offset:50752
	v_cvt_pk_bf16_f32 v188, v236, v237
	v_cvt_pk_bf16_f32 v189, v238, v239
	v_cvt_pk_bf16_f32 v190, v240, v241
	v_cvt_pk_bf16_f32 v191, v242, v243
	v_add_f32_e32 v236, v236, v237
	v_add_f32_e32 v238, v238, v239
	v_add_f32_e32 v240, v240, v241
	v_add_f32_e32 v242, v242, v243
	v_mfma_f32_32x32x16_bf16 v[52:67], v[156:159], v[114:117], 0
	ds_read_b64_tr_b16 v[212:213], v244 offset:52224
	s_waitcnt lgkmcnt(12)
	ds_read_b64_tr_b16 v[214:215], v244 offset:53760
	ds_read_b64_tr_b16 v[140:141], v244 offset:55296
	s_waitcnt lgkmcnt(12)
	ds_read_b64_tr_b16 v[142:143], v244 offset:56832
	v_add_f32_e32 v236, v236, v238
	v_add_f32_e32 v240, v240, v242
	v_add_f32_e32 v236, v236, v240
	v_add_f32_e32 v196, v196, v236
	v_mfma_f32_32x32x16_bf16 v[52:67], v[160:163], v[118:121], v[52:67]
	ds_read_b64_tr_b16 v[216:217], v244 offset:52288
	s_waitcnt lgkmcnt(12)
	ds_read_b64_tr_b16 v[218:219], v244 offset:53824
	ds_read_b64_tr_b16 v[144:145], v244 offset:55360
	s_waitcnt lgkmcnt(12)
	ds_read_b64_tr_b16 v[146:147], v244 offset:56896
	v_exp_f32_e32 v236, v228
	v_exp_f32_e32 v237, v229
	v_exp_f32_e32 v238, v230
	v_exp_f32_e32 v239, v231
	v_exp_f32_e32 v240, v232
	v_exp_f32_e32 v241, v233
	v_exp_f32_e32 v242, v234
	v_exp_f32_e32 v243, v235
	v_mfma_f32_32x32x16_bf16 v[52:67], v[164:167], v[122:125], v[52:67]
	ds_read_b64_tr_b16 v[148:149], v244 offset:58368
	s_waitcnt lgkmcnt(12)
	ds_read_b64_tr_b16 v[150:151], v244 offset:59904
	v_cvt_pk_bf16_f32 v192, v236, v237
	v_cvt_pk_bf16_f32 v193, v238, v239
	v_cvt_pk_bf16_f32 v194, v240, v241
	v_cvt_pk_bf16_f32 v195, v242, v243
	v_add_f32_e32 v236, v236, v237
	v_add_f32_e32 v238, v238, v239
	v_add_f32_e32 v240, v240, v241
	v_add_f32_e32 v242, v242, v243
	v_mfma_f32_32x32x16_bf16 v[52:67], v[168:171], v[126:129], v[52:67]
	ds_read_b64_tr_b16 v[152:153], v244 offset:58432
	s_waitcnt lgkmcnt(12)
	ds_read_b64_tr_b16 v[154:155], v244 offset:59968
	v_add_f32_e32 v236, v236, v238
	v_add_f32_e32 v240, v240, v242
	v_add_f32_e32 v236, v236, v240
	v_add_f32_e32 v196, v196, v236
	v_mfma_f32_32x32x16_bf16 v[20:35], v[84:87], v[180:183], v[20:35]
	v_exp_f32_e32 v236, v36
	v_exp_f32_e32 v237, v37
	v_exp_f32_e32 v238, v38
	v_exp_f32_e32 v239, v39
	v_exp_f32_e32 v240, v40
	v_exp_f32_e32 v241, v41
	v_exp_f32_e32 v242, v42
	v_exp_f32_e32 v243, v43
	v_mfma_f32_32x32x16_bf16 v[4:19], v[88:91], v[180:183], v[4:19]
	v_cvt_pk_bf16_f32 v180, v236, v237
	v_cvt_pk_bf16_f32 v181, v238, v239
	v_cvt_pk_bf16_f32 v182, v240, v241
	v_cvt_pk_bf16_f32 v183, v242, v243
	v_add_f32_e32 v236, v236, v237
	v_add_f32_e32 v238, v238, v239
	v_add_f32_e32 v240, v240, v241
	v_add_f32_e32 v242, v242, v243
	v_mfma_f32_32x32x16_bf16 v[20:35], v[92:95], v[184:187], v[20:35]
	v_add_f32_e32 v236, v236, v238
	v_add_f32_e32 v240, v240, v242
	v_add_f32_e32 v197, v236, v240
	v_exp_f32_e32 v236, v44
	v_mfma_f32_32x32x16_bf16 v[4:19], v[96:99], v[184:187], v[4:19]
	v_exp_f32_e32 v237, v45
	v_exp_f32_e32 v238, v46
	v_exp_f32_e32 v239, v47
	v_exp_f32_e32 v240, v48
	v_exp_f32_e32 v241, v49
	v_exp_f32_e32 v242, v50
	v_exp_f32_e32 v243, v51
	v_cvt_pk_bf16_f32 v184, v236, v237
	v_mfma_f32_32x32x16_bf16 v[20:35], v[100:103], v[188:191], v[20:35]
	v_cvt_pk_bf16_f32 v185, v238, v239
	v_cvt_pk_bf16_f32 v186, v240, v241
	v_cvt_pk_bf16_f32 v187, v242, v243
	v_add_f32_e32 v236, v236, v237
	v_add_f32_e32 v238, v238, v239
	v_add_f32_e32 v240, v240, v241
	v_add_f32_e32 v242, v242, v243
	v_add_f32_e32 v236, v236, v238
	v_mfma_f32_32x32x16_bf16 v[4:19], v[104:107], v[188:191], v[4:19]
	v_add_f32_e32 v240, v240, v242
	v_add_f32_e32 v236, v236, v240
	v_add_f32_e32 v197, v197, v236
	v_exp_f32_e32 v236, v52
	v_mfma_f32_32x32x16_bf16 v[20:35], v[108:111], v[192:195], v[20:35]
	v_exp_f32_e32 v237, v53
	v_exp_f32_e32 v238, v54
	v_exp_f32_e32 v239, v55
	v_exp_f32_e32 v240, v56
	v_exp_f32_e32 v241, v57
	v_exp_f32_e32 v242, v58
	v_exp_f32_e32 v243, v59
	v_cvt_pk_bf16_f32 v188, v236, v237
	v_mfma_f32_32x32x16_bf16 v[4:19], v[130:133], v[192:195], v[4:19]
	v_cvt_pk_bf16_f32 v189, v238, v239
	v_cvt_pk_bf16_f32 v190, v240, v241
	v_cvt_pk_bf16_f32 v191, v242, v243
	v_add_f32_e32 v236, v236, v237
	v_add_f32_e32 v238, v238, v239
	v_add_f32_e32 v240, v240, v241
	v_add_f32_e32 v242, v242, v243
	v_add_f32_e32 v236, v236, v238
	v_mfma_f32_32x32x16_bf16 v[20:35], v[204:207], v[180:183], v[20:35]
	v_add_f32_e32 v240, v240, v242
	v_add_f32_e32 v236, v236, v240
	v_add_f32_e32 v197, v197, v236
	v_exp_f32_e32 v236, v60
	s_waitcnt lgkmcnt(12)
	v_mfma_f32_32x32x16_bf16 v[4:19], v[208:211], v[180:183], v[4:19]
	v_exp_f32_e32 v237, v61
	v_exp_f32_e32 v238, v62
	v_exp_f32_e32 v239, v63
	v_exp_f32_e32 v240, v64
	v_exp_f32_e32 v241, v65
	v_exp_f32_e32 v242, v66
	v_exp_f32_e32 v243, v67
	v_cvt_pk_bf16_f32 v192, v236, v237
	s_waitcnt lgkmcnt(10)
	v_mfma_f32_32x32x16_bf16 v[20:35], v[212:215], v[184:187], v[20:35]
	v_cvt_pk_bf16_f32 v193, v238, v239
	v_cvt_pk_bf16_f32 v194, v240, v241
	v_cvt_pk_bf16_f32 v195, v242, v243
	v_add_f32_e32 v236, v236, v237
	v_add_f32_e32 v238, v238, v239
	v_add_f32_e32 v240, v240, v241
	v_add_f32_e32 v242, v242, v243
	v_add_f32_e32 v236, v236, v238
	s_waitcnt lgkmcnt(6)
	v_mfma_f32_32x32x16_bf16 v[4:19], v[216:219], v[184:187], v[4:19]
	v_add_f32_e32 v240, v240, v242
	v_add_f32_e32 v236, v236, v240
	v_add_f32_e32 v197, v197, v236
	v_mfma_f32_32x32x16_bf16 v[20:35], v[140:143], v[188:191], v[20:35]
	v_add_f32_e32 v196, v196, v197
	v_add_f32_e32 v2, v179, v196
	s_waitcnt lgkmcnt(4)
	v_mfma_f32_32x32x16_bf16 v[4:19], v[144:147], v[188:191], v[4:19]
	v_mov_b32_e32 v236, v2
	v_mov_b32_e32 v237, v2
	s_waitcnt lgkmcnt(2)
	v_mfma_f32_32x32x16_bf16 v[20:35], v[148:151], v[192:195], v[20:35]
	v_permlane32_swap_b32_e32 v236, v237
	s_waitcnt lgkmcnt(0)
	v_mfma_f32_32x32x16_bf16 v[4:19], v[152:155], v[192:195], v[4:19]
	v_max_f32_e32 v237, v237, v237
	v_max_f32_e32 v236, v236, v236
	v_max_f32_e32 v236, v236, v237
	v_cmp_lt_f32_e32 vcc, s15, v236
	s_cbranch_vccz .Lwin_a2_noshift
	s_nop 7
	s_nop 7
	v_cndmask_b32_e32 v236, 0, v248, vcc
	v_cndmask_b32_e32 v238, 1.0, v249, vcc
	v_add_f32_e32 v178, v178, v236
	v_mul_f32_e32 v2, v2, v238
	v_pk_mul_f32 v[4:5], v[4:5], v[238:239] op_sel_hi:[1,0]
	v_pk_mul_f32 v[6:7], v[6:7], v[238:239] op_sel_hi:[1,0]
	v_pk_mul_f32 v[8:9], v[8:9], v[238:239] op_sel_hi:[1,0]
	v_pk_mul_f32 v[10:11], v[10:11], v[238:239] op_sel_hi:[1,0]
	v_pk_mul_f32 v[12:13], v[12:13], v[238:239] op_sel_hi:[1,0]
	v_pk_mul_f32 v[14:15], v[14:15], v[238:239] op_sel_hi:[1,0]
	v_pk_mul_f32 v[16:17], v[16:17], v[238:239] op_sel_hi:[1,0]
	v_pk_mul_f32 v[18:19], v[18:19], v[238:239] op_sel_hi:[1,0]
	v_pk_mul_f32 v[20:21], v[20:21], v[238:239] op_sel_hi:[1,0]
	v_pk_mul_f32 v[22:23], v[22:23], v[238:239] op_sel_hi:[1,0]
	v_pk_mul_f32 v[24:25], v[24:25], v[238:239] op_sel_hi:[1,0]
	v_pk_mul_f32 v[26:27], v[26:27], v[238:239] op_sel_hi:[1,0]
	v_pk_mul_f32 v[28:29], v[28:29], v[238:239] op_sel_hi:[1,0]
	v_pk_mul_f32 v[30:31], v[30:31], v[238:239] op_sel_hi:[1,0]
	v_pk_mul_f32 v[32:33], v[32:33], v[238:239] op_sel_hi:[1,0]
	v_pk_mul_f32 v[34:35], v[34:35], v[238:239] op_sel_hi:[1,0]
.Lwin_a2_noshift:
	v_mov_b32_e32 v179, v2
	s_branch .LBB0_1397
